# static priority 3 (instead of 1) for waves 0-3
# speedup vs baseline: 1.0057x; 1.0002x over previous
.LBB0_7:
	v_cmp_lt_u32_e32 vcc, 0xff, v0
	s_setprio 3
	s_cbranch_vccz .Lprio_lo
	s_setprio 0
